# nt_loads_p0abc
# baseline (speedup 1.0000x reference)
.LBB0_50:
	v_ashrrev_i32_e32 v7, 31, v6
	v_lshl_add_u64 v[16:17], v[6:7], 4, s[10:11]
	global_load_dwordx4 v[8:11], v[16:17], off nt
	global_load_dwordx4 v[12:15], v[16:17], off offset:16 nt
	v_add_u32_e32 v3, s2, v3
	v_cmp_lt_i32_e64 s[0:1], s18, v3
	v_add_u32_e32 v6, s3, v6
	s_or_b64 s[14:15], s[0:1], s[14:15]
	s_waitcnt vmcnt(1)
	v_cvt_pk_bf16_f32 v8, v8, v9
	v_cvt_pk_bf16_f32 v9, v10, v11
	s_waitcnt vmcnt(0)
	v_cvt_pk_bf16_f32 v10, v12, v13
	v_cvt_pk_bf16_f32 v11, v14, v15
	global_store_dwordx4 v[4:5], v[8:11], off
	v_lshl_add_u64 v[4:5], v[4:5], 0, s[12:13]
	s_andn2_b64 exec, exec, s[14:15]
	s_cbranch_execnz .LBB0_50

.LBB0_53:
	v_ashrrev_i32_e32 v11, 31, v10
	v_lshl_add_u64 v[20:21], v[10:11], 4, s[8:9]
	global_load_dwordx4 v[12:15], v[20:21], off nt
	global_load_dwordx4 v[16:19], v[20:21], off offset:16 nt
	v_add_u32_e32 v1, s2, v1
	v_cmp_lt_i32_e32 vcc, s12, v1
	v_add_u32_e32 v10, s3, v10
	s_or_b64 s[10:11], vcc, s[10:11]
	s_waitcnt vmcnt(1)
	v_cvt_pk_bf16_f32 v12, v12, v13
	v_cvt_pk_bf16_f32 v13, v14, v15
	s_waitcnt vmcnt(0)
	v_cvt_pk_bf16_f32 v14, v16, v17
	v_cvt_pk_bf16_f32 v15, v18, v19
	global_store_dwordx4 v[8:9], v[12:15], off
	v_lshl_add_u64 v[8:9], v[8:9], 0, s[6:7]
	s_andn2_b64 exec, exec, s[10:11]
	s_cbranch_execnz .LBB0_53
	s_or_b64 exec, exec, s[10:11]
	s_load_dwordx2 s[4:5], s[4:5], 0x18
	s_mov_b64 s[8:9], 0x1f7c0000
	v_lshl_add_u64 v[6:7], v[6:7], 0, s[8:9]
	s_mov_b64 s[8:9], 0
	s_mov_b32 s10, 0x7ffff
.LBB0_55:
	v_ashrrev_i32_e32 v5, 31, v4
	s_waitcnt lgkmcnt(0)
	v_lshl_add_u64 v[16:17], v[4:5], 4, s[4:5]
	global_load_dwordx4 v[8:11], v[16:17], off nt
	global_load_dwordx4 v[12:15], v[16:17], off offset:16 nt
	v_add_u32_e32 v2, s2, v2
	v_cmp_lt_i32_e32 vcc, s10, v2
	v_add_u32_e32 v4, s3, v4
	s_or_b64 s[8:9], vcc, s[8:9]
	s_waitcnt vmcnt(1)
	v_cvt_pk_bf16_f32 v8, v8, v9
	v_cvt_pk_bf16_f32 v9, v10, v11
	s_waitcnt vmcnt(0)
	v_cvt_pk_bf16_f32 v10, v12, v13
	v_cvt_pk_bf16_f32 v11, v14, v15
	global_store_dwordx4 v[6:7], v[8:11], off
	v_lshl_add_u64 v[6:7], v[6:7], 0, s[6:7]
	s_andn2_b64 exec, exec, s[8:9]
	s_cbranch_execnz .LBB0_55

.LBB0_67:
	v_add_u32_e32 v25, s10, v7
	v_mad_i64_i32 v[26:27], s[16:17], v25, s14, v[16:17]
	global_load_dwordx4 v[26:29], v[26:27], off nt
	v_add_u32_e32 v30, 4, v25
	v_add_u32_e32 v31, 8, v25
	v_add_u32_e32 v32, 12, v25
	v_add_u32_e32 v33, 16, v25
	v_add_u32_e32 v37, 20, v25
	v_add_u32_e32 v38, 24, v25
	v_add_u32_e32 v25, 28, v25
	v_mad_i64_i32 v[62:63], s[16:17], v30, s14, v[16:17]
	v_mad_i64_i32 v[64:65], s[16:17], v31, s14, v[16:17]
	v_mad_i64_i32 v[66:67], s[16:17], v32, s14, v[16:17]
	v_mad_i64_i32 v[68:69], s[16:17], v33, s14, v[16:17]
	v_mad_i64_i32 v[70:71], s[16:17], v37, s14, v[16:17]
	v_mad_i64_i32 v[72:73], s[16:17], v38, s14, v[16:17]
	v_mad_i64_i32 v[74:75], s[16:17], v25, s14, v[16:17]
	global_load_dwordx4 v[30:33], v[62:63], off nt
	global_load_dwordx4 v[38:41], v[64:65], off nt
	global_load_dwordx4 v[42:45], v[66:67], off nt
	global_load_dwordx4 v[46:49], v[68:69], off nt
	global_load_dwordx4 v[50:53], v[70:71], off nt
	global_load_dwordx4 v[54:57], v[72:73], off nt
	global_load_dwordx4 v[58:61], v[74:75], off nt
	ds_read2_b32 v[62:63], v24 offset1:4
	ds_read2_b32 v[64:65], v24 offset0:8 offset1:12
	v_add_u32_e32 v25, 0x2000, v24
	v_add_u32_e32 v37, 0x4000, v24
	ds_read2_b32 v[66:67], v24 offset0:16 offset1:20
	ds_read2_b32 v[68:69], v24 offset0:24 offset1:28
	ds_read2_b32 v[70:71], v25 offset1:4
	ds_read2_b32 v[72:73], v37 offset1:4
	ds_read2_b32 v[74:75], v25 offset0:8 offset1:12
	ds_read2_b32 v[76:77], v37 offset0:8 offset1:12
	ds_read2_b32 v[78:79], v25 offset0:16 offset1:20
	ds_read2_b32 v[80:81], v37 offset0:16 offset1:20
	ds_read2_b32 v[82:83], v25 offset0:24 offset1:28
	ds_read2_b32 v[84:85], v37 offset0:24 offset1:28
	s_waitcnt lgkmcnt(11)
	v_mov_b32_e32 v86, v63
	s_waitcnt lgkmcnt(7)
	v_mov_b32_e32 v94, v71
	s_waitcnt lgkmcnt(6)
	v_mov_b32_e32 v96, v73
	v_mov_b32_e32 v88, v65
	s_waitcnt lgkmcnt(5)
	v_mov_b32_e32 v98, v75
	s_waitcnt lgkmcnt(4)
	v_mov_b32_e32 v100, v77
	v_mov_b32_e32 v90, v67
	s_waitcnt lgkmcnt(3)
	v_mov_b32_e32 v102, v79
	s_waitcnt lgkmcnt(2)
	v_mov_b32_e32 v104, v81
	s_add_i32 s10, s10, 32
	v_mov_b32_e32 v92, v69
	s_waitcnt lgkmcnt(1)
	v_mov_b32_e32 v106, v83
	s_waitcnt lgkmcnt(0)
	v_mov_b32_e32 v108, v85
	v_add_u32_e32 v24, 0x80, v24
	s_cmpk_eq_i32 s10, 0x100
	s_waitcnt vmcnt(7)
	v_pk_fma_f32 v[22:23], v[26:27], v[62:63], v[22:23] op_sel_hi:[1,0,1]
	v_pk_fma_f32 v[14:15], v[28:29], v[62:63], v[14:15] op_sel_hi:[1,0,1]
	v_pk_fma_f32 v[20:21], v[26:27], v[70:71], v[20:21] op_sel_hi:[1,0,1]
	v_pk_fma_f32 v[12:13], v[28:29], v[70:71], v[12:13] op_sel_hi:[1,0,1]
	v_pk_fma_f32 v[18:19], v[26:27], v[72:73], v[18:19] op_sel_hi:[1,0,1]
	v_pk_fma_f32 v[10:11], v[28:29], v[72:73], v[10:11] op_sel_hi:[1,0,1]
	s_waitcnt vmcnt(6)
	v_pk_fma_f32 v[14:15], v[32:33], v[86:87], v[14:15] op_sel_hi:[1,0,1]
	v_pk_fma_f32 v[22:23], v[30:31], v[86:87], v[22:23] op_sel_hi:[1,0,1]
	v_pk_fma_f32 v[12:13], v[32:33], v[94:95], v[12:13] op_sel_hi:[1,0,1]
	v_pk_fma_f32 v[20:21], v[30:31], v[94:95], v[20:21] op_sel_hi:[1,0,1]
	v_pk_fma_f32 v[10:11], v[32:33], v[96:97], v[10:11] op_sel_hi:[1,0,1]
	v_pk_fma_f32 v[18:19], v[30:31], v[96:97], v[18:19] op_sel_hi:[1,0,1]
	s_waitcnt vmcnt(5)
	v_pk_fma_f32 v[22:23], v[38:39], v[64:65], v[22:23] op_sel_hi:[1,0,1]
	v_pk_fma_f32 v[14:15], v[40:41], v[64:65], v[14:15] op_sel_hi:[1,0,1]
	v_pk_fma_f32 v[20:21], v[38:39], v[74:75], v[20:21] op_sel_hi:[1,0,1]
	v_pk_fma_f32 v[12:13], v[40:41], v[74:75], v[12:13] op_sel_hi:[1,0,1]
	v_pk_fma_f32 v[18:19], v[38:39], v[76:77], v[18:19] op_sel_hi:[1,0,1]
	v_pk_fma_f32 v[10:11], v[40:41], v[76:77], v[10:11] op_sel_hi:[1,0,1]
	s_waitcnt vmcnt(4)
	v_pk_fma_f32 v[14:15], v[44:45], v[88:89], v[14:15] op_sel_hi:[1,0,1]
	v_pk_fma_f32 v[22:23], v[42:43], v[88:89], v[22:23] op_sel_hi:[1,0,1]
	v_pk_fma_f32 v[12:13], v[44:45], v[98:99], v[12:13] op_sel_hi:[1,0,1]
	v_pk_fma_f32 v[20:21], v[42:43], v[98:99], v[20:21] op_sel_hi:[1,0,1]
	v_pk_fma_f32 v[10:11], v[44:45], v[100:101], v[10:11] op_sel_hi:[1,0,1]
	v_pk_fma_f32 v[18:19], v[42:43], v[100:101], v[18:19] op_sel_hi:[1,0,1]
	s_waitcnt vmcnt(3)
	v_pk_fma_f32 v[22:23], v[46:47], v[66:67], v[22:23] op_sel_hi:[1,0,1]
	v_pk_fma_f32 v[14:15], v[48:49], v[66:67], v[14:15] op_sel_hi:[1,0,1]
	v_pk_fma_f32 v[20:21], v[46:47], v[78:79], v[20:21] op_sel_hi:[1,0,1]
	v_pk_fma_f32 v[12:13], v[48:49], v[78:79], v[12:13] op_sel_hi:[1,0,1]
	v_pk_fma_f32 v[18:19], v[46:47], v[80:81], v[18:19] op_sel_hi:[1,0,1]
	v_pk_fma_f32 v[10:11], v[48:49], v[80:81], v[10:11] op_sel_hi:[1,0,1]
	s_waitcnt vmcnt(2)
	v_pk_fma_f32 v[14:15], v[52:53], v[90:91], v[14:15] op_sel_hi:[1,0,1]
	v_pk_fma_f32 v[22:23], v[50:51], v[90:91], v[22:23] op_sel_hi:[1,0,1]
	v_pk_fma_f32 v[12:13], v[52:53], v[102:103], v[12:13] op_sel_hi:[1,0,1]
	v_pk_fma_f32 v[20:21], v[50:51], v[102:103], v[20:21] op_sel_hi:[1,0,1]
	v_pk_fma_f32 v[10:11], v[52:53], v[104:105], v[10:11] op_sel_hi:[1,0,1]
	v_pk_fma_f32 v[18:19], v[50:51], v[104:105], v[18:19] op_sel_hi:[1,0,1]
	s_waitcnt vmcnt(1)
	v_pk_fma_f32 v[22:23], v[54:55], v[68:69], v[22:23] op_sel_hi:[1,0,1]
	v_pk_fma_f32 v[14:15], v[56:57], v[68:69], v[14:15] op_sel_hi:[1,0,1]
	v_pk_fma_f32 v[20:21], v[54:55], v[82:83], v[20:21] op_sel_hi:[1,0,1]
	v_pk_fma_f32 v[12:13], v[56:57], v[82:83], v[12:13] op_sel_hi:[1,0,1]
	v_pk_fma_f32 v[18:19], v[54:55], v[84:85], v[18:19] op_sel_hi:[1,0,1]
	v_pk_fma_f32 v[10:11], v[56:57], v[84:85], v[10:11] op_sel_hi:[1,0,1]
	s_waitcnt vmcnt(0)
	v_pk_fma_f32 v[14:15], v[60:61], v[92:93], v[14:15] op_sel_hi:[1,0,1]
	v_pk_fma_f32 v[22:23], v[58:59], v[92:93], v[22:23] op_sel_hi:[1,0,1]
	v_pk_fma_f32 v[12:13], v[60:61], v[106:107], v[12:13] op_sel_hi:[1,0,1]
	v_pk_fma_f32 v[20:21], v[58:59], v[106:107], v[20:21] op_sel_hi:[1,0,1]
	v_pk_fma_f32 v[10:11], v[60:61], v[108:109], v[10:11] op_sel_hi:[1,0,1]
	v_pk_fma_f32 v[18:19], v[58:59], v[108:109], v[18:19] op_sel_hi:[1,0,1]
	s_cbranch_scc0 .LBB0_67
	ds_bpermute_b32 v16, v1, v22
	ds_bpermute_b32 v17, v1, v23
	ds_bpermute_b32 v24, v1, v20
	ds_bpermute_b32 v26, v1, v18
	ds_bpermute_b32 v25, v1, v21
	ds_bpermute_b32 v27, v1, v19
	ds_bpermute_b32 v28, v1, v14
	ds_bpermute_b32 v29, v1, v15
	ds_bpermute_b32 v30, v1, v12
	ds_bpermute_b32 v32, v1, v10
	ds_bpermute_b32 v31, v1, v13
	ds_bpermute_b32 v33, v1, v11
	s_waitcnt lgkmcnt(10)
	v_pk_add_f32 v[16:17], v[22:23], v[16:17]
	s_waitcnt lgkmcnt(7)
	v_pk_add_f32 v[20:21], v[20:21], v[24:25]
	s_waitcnt lgkmcnt(6)
	v_pk_add_f32 v[18:19], v[18:19], v[26:27]
	s_waitcnt lgkmcnt(4)
	v_pk_add_f32 v[14:15], v[14:15], v[28:29]
	s_waitcnt lgkmcnt(1)
	v_pk_add_f32 v[12:13], v[12:13], v[30:31]
	s_waitcnt lgkmcnt(0)
	v_pk_add_f32 v[10:11], v[10:11], v[32:33]
	ds_bpermute_b32 v22, v3, v16
	ds_bpermute_b32 v23, v3, v17
	ds_bpermute_b32 v24, v3, v20
	ds_bpermute_b32 v25, v3, v21
	ds_bpermute_b32 v26, v3, v18
	ds_bpermute_b32 v27, v3, v19
	ds_bpermute_b32 v28, v3, v14
	ds_bpermute_b32 v29, v3, v15
	ds_bpermute_b32 v30, v3, v12
	ds_bpermute_b32 v31, v3, v13
	ds_bpermute_b32 v32, v3, v10
	ds_bpermute_b32 v33, v3, v11
	s_and_saveexec_b64 s[10:11], vcc
	s_cbranch_execz .LBB0_70
	s_waitcnt lgkmcnt(6)
	v_pk_add_f32 v[38:39], v[18:19], v[26:27]
	s_waitcnt lgkmcnt(4)
	v_pk_add_f32 v[18:19], v[14:15], v[28:29]
	v_pk_add_f32 v[16:17], v[16:17], v[22:23]
	s_waitcnt lgkmcnt(0)
	v_pk_add_f32 v[40:41], v[10:11], v[32:33]
	v_pk_add_f32 v[12:13], v[12:13], v[30:31]
	v_pk_add_f32 v[10:11], v[20:21], v[24:25]
	ds_write_b128 v35, v[16:19] offset:32768
	ds_write_b128 v35, v[10:13] offset:33024
	ds_write_b128 v35, v[38:41] offset:33280
